# baseline (speedup 1.0000x reference)
; DEV int lv(int x) { asm volatile("" : "+v"(x)); return x; }
; DEV float wave_sum(float v) { for (int o = 32; o >= 1; o >>= 1) v += __shfl_xor(v, o); return v; }
; DEV void post_rows(const Params& p, const float* __restrict__ xsrc, const float* __restrict__ g, bool final) {
;   const int tid_ = lv(threadIdx.x), wid = tid_ >> 6, lane = tid_ & 63;
;   const bf16_t* mb = (const bf16_t*)(p.ws + WS_M); bf16_t* xb = (bf16_t*)(p.ws + WS_XB); float* rstd = (float*)(p.ws + WS_RSTD);
;   for (int row = blockIdx.x * 8 + wid; row < SEQ; row += gridDim.x * 8) {
;     float mv[32]; float ss = 0;
; #pragma unroll
;     for (int c = 0; c < 4; ++c) { const int idx = c * 512 + lane * 8; const u32x4 w = *reinterpret_cast<const u32x4*>(mb + (size_t)row * DM + idx);
; #pragma unroll
;       for (int e = 0; e < 4; ++e) { const float lo = __uint_as_float(w[e] << 16), hi = __uint_as_float(w[e] & 0xffff0000u);
;         mv[c * 8 + 2 * e] = lo; mv[c * 8 + 2 * e + 1] = hi; ss += lo * lo + hi * hi; } }
;     ss = wave_sum(ss);
;     const float rm = rsqrtf(ss * (1.f / DM) + EPS);
;     float sx = 0;
; #pragma unroll
;     for (int c = 0; c < 4; ++c) { const int idx = c * 512 + lane * 8;
;       float xo[8];
;       if (xsrc) { const f32x4 a = *reinterpret_cast<const f32x4*>(xsrc + (size_t)row * DM + idx), b = *reinterpret_cast<const f32x4*>(xsrc + (size_t)row * DM + idx + 4);
; #pragma unroll
;         for (int e = 0; e < 4; ++e) { xo[e] = a[e]; xo[4 + e] = b[e]; } }
;       else { const u32x4 w = *reinterpret_cast<const u32x4*>(xb + (size_t)row * DM + idx);
; #pragma unroll
;         for (int e = 0; e < 4; ++e) { xo[2 * e] = __uint_as_float(w[e] << 16); xo[2 * e + 1] = __uint_as_float(w[e] & 0xffff0000u); } }
;       const f32x4 g0 = *reinterpret_cast<const f32x4*>(g + idx), g1 = *reinterpret_cast<const f32x4*>(g + idx + 4);
.LBB0_552:
	s_or_b64 exec, exec, s[0:1]
	s_waitcnt lgkmcnt(0)
	v_mov_b32_e32 v0, v210
	s_barrier
	v_readlane_b32 s0, v255, 11
	s_lshl_b32 s76, s0, 11
	v_ashrrev_i32_e32 v1, 6, v0
	v_add_u32_e32 v32, s70, v1
	s_movk_i32 s0, 0x4000
	v_cmp_gt_i32_e32 vcc, s0, v32
	s_and_saveexec_b64 s[6:7], vcc
	s_cbranch_execz .LBB0_557
	v_readlane_b32 s8, v252, 16
	s_lshl_b64 s[0:1], s[76:77], 2
	v_readlane_b32 s12, v252, 20
	v_readlane_b32 s13, v252, 21
	s_add_u32 s0, s12, s0
	v_and_b32_e32 v33, 63, v0
	s_addc_u32 s1, s13, s1
	v_lshlrev_b32_e32 v24, 5, v33
	global_load_dwordx4 v[0:3], v24, s[0:1]
	global_load_dwordx4 v[4:7], v24, s[0:1] offset:16
	global_load_dwordx4 v[8:11], v24, s[0:1] offset:2048
	global_load_dwordx4 v[12:15], v24, s[0:1] offset:2064
	v_or_b32_e32 v20, 0x1000, v24
	v_or_b32_e32 v28, 0x1800, v24
	global_load_dwordx4 v[16:19], v20, s[0:1]
	s_nop 0
	global_load_dwordx4 v[20:23], v20, s[0:1] offset:16
	s_nop 0
	global_load_dwordx4 v[24:27], v28, s[0:1]
	s_nop 0
	global_load_dwordx4 v[28:31], v28, s[0:1] offset:16
	v_readlane_b32 s0, v252, 34
	v_readlane_b32 s9, v252, 17
	v_lshlrev_b32_e32 v192, 4, v33
	v_readlane_b32 s1, v252, 35
	v_cmp_eq_u32_e32 vcc, 0, v33
	v_lshl_add_u64 v[36:37], s[66:67], 0, v[192:193]
	v_lshl_add_u64 v[34:35], s[0:1], 0, v[192:193]
	s_mov_b64 s[8:9], 0
	v_readlane_b32 s10, v252, 18
	v_readlane_b32 s11, v252, 19
	v_readlane_b32 s14, v252, 22
	v_readlane_b32 s15, v252, 23
	v_readlane_b32 s16, v252, 24
	v_readlane_b32 s17, v252, 25
	v_readlane_b32 s18, v252, 26
	v_readlane_b32 s19, v252, 27
	v_readlane_b32 s20, v252, 28
	v_readlane_b32 s21, v252, 29
	v_readlane_b32 s22, v252, 30
	v_readlane_b32 s23, v252, 31
	v_mov_b32_e32 v164, v32
	v_ashrrev_i32_e32 v165, 31, v164
	v_lshlrev_b64 v[162:163], 12, v[164:165]
	v_lshl_add_u64 v[160:161], v[34:35], 0, v[162:163]
	v_lshl_add_u64 v[162:163], v[36:37], 0, v[162:163]
	global_load_dwordx4 v[128:131], v[160:161], off
	global_load_dwordx4 v[132:135], v[162:163], off
	global_load_dwordx4 v[136:139], v[160:161], off offset:1024
	global_load_dwordx4 v[140:143], v[160:161], off offset:2048
	global_load_dwordx4 v[144:147], v[160:161], off offset:3072
	global_load_dwordx4 v[148:151], v[162:163], off offset:1024
	global_load_dwordx4 v[152:155], v[162:163], off offset:2048
	global_load_dwordx4 v[156:159], v[162:163], off offset:3072
	s_waitcnt vmcnt(0)
	s_branch .LBB0_555

; DEV float wave_sum(float v) { for (int o = 32; o >= 1; o >>= 1) v += __shfl_xor(v, o); return v; }
; DEV void post_rows(const Params& p, const float* __restrict__ xsrc, const float* __restrict__ g, bool final) {
;     ...
;   for (int row = blockIdx.x * 8 + wid; row < SEQ; row += gridDim.x * 8) {
;     float mv[32]; float ss = 0;
; #pragma unroll
;     for (int c = 0; c < 4; ++c) { const int idx = c * 512 + lane * 8; const u32x4 w = *reinterpret_cast<const u32x4*>(mb + (size_t)row * DM + idx);
; #pragma unroll
;       for (int e = 0; e < 4; ++e) { const float lo = __uint_as_float(w[e] << 16), hi = __uint_as_float(w[e] & 0xffff0000u);
;         mv[c * 8 + 2 * e] = lo; mv[c * 8 + 2 * e + 1] = hi; ss += lo * lo + hi * hi; } }
;     ss = wave_sum(ss);
;     const float rm = rsqrtf(ss * (1.f / DM) + EPS);
;     float sx = 0;
; #pragma unroll
;     for (int c = 0; c < 4; ++c) { const int idx = c * 512 + lane * 8;
;       float xo[8];
;       if (xsrc) { const f32x4 a = *reinterpret_cast<const f32x4*>(xsrc + (size_t)row * DM + idx), b = *reinterpret_cast<const f32x4*>(xsrc + (size_t)row * DM + idx + 4);
; #pragma unroll
;         for (int e = 0; e < 4; ++e) { xo[e] = a[e]; xo[4 + e] = b[e]; } }
;       else { const u32x4 w = *reinterpret_cast<const u32x4*>(xb + (size_t)row * DM + idx);
; #pragma unroll
;         for (int e = 0; e < 4; ++e) { xo[2 * e] = __uint_as_float(w[e] << 16); xo[2 * e + 1] = __uint_as_float(w[e] & 0xffff0000u); } }
.LBB0_555:
	v_ashrrev_i32_e32 v33, 31, v32
	v_lshlrev_b64 v[38:39], 12, v[32:33]
	s_waitcnt lgkmcnt(0)
	v_lshl_add_u64 v[38:39], v[36:37], 0, v[38:39]
	s_waitcnt vmcnt(4)
	v_mov_b64_e32 v[40:41], v[128:129]
	v_mov_b64_e32 v[42:43], v[130:131]
	v_mov_b64_e32 v[44:45], v[132:133]
	v_mov_b64_e32 v[46:47], v[134:135]
	v_mov_b64_e32 v[48:49], v[136:137]
	v_mov_b64_e32 v[50:51], v[138:139]
	v_mov_b64_e32 v[52:53], v[140:141]
	v_mov_b64_e32 v[54:55], v[142:143]
	v_mov_b64_e32 v[56:57], v[144:145]
	v_mov_b64_e32 v[58:59], v[146:147]
	v_mov_b64_e32 v[60:61], v[148:149]
	v_mov_b64_e32 v[62:63], v[150:151]
	v_mov_b64_e32 v[64:65], v[152:153]
	v_mov_b64_e32 v[66:67], v[154:155]
	v_mov_b64_e32 v[68:69], v[156:157]
	v_mov_b64_e32 v[70:71], v[158:159]
	v_readlane_b32 s0, v253, 39
	s_nop 1
	v_add_u32_e32 v164, s0, v32
	v_ashrrev_i32_e32 v165, 31, v164
	v_lshlrev_b64 v[162:163], 12, v[164:165]
	v_lshl_add_u64 v[160:161], v[34:35], 0, v[162:163]
	v_lshl_add_u64 v[162:163], v[36:37], 0, v[162:163]
	global_load_dwordx4 v[128:131], v[160:161], off
	global_load_dwordx4 v[132:135], v[162:163], off
	global_load_dwordx4 v[136:139], v[160:161], off offset:1024
	global_load_dwordx4 v[140:143], v[160:161], off offset:2048
	global_load_dwordx4 v[144:147], v[160:161], off offset:3072
	global_load_dwordx4 v[148:151], v[162:163], off offset:1024
	global_load_dwordx4 v[152:155], v[162:163], off offset:2048
	global_load_dwordx4 v[156:159], v[162:163], off offset:3072
	v_lshlrev_b32_e32 v74, 16, v47
	v_and_b32_e32 v75, 0xffff0000, v47
	v_lshlrev_b32_e32 v78, 16, v46
	v_and_b32_e32 v79, 0xffff0000, v46
	v_lshlrev_b32_e32 v46, 16, v41
	v_and_b32_e32 v47, 0xffff0000, v41
	v_lshlrev_b32_e32 v82, 16, v40
	v_and_b32_e32 v83, 0xffff0000, v40
	v_lshlrev_b32_e32 v72, 16, v43
	v_and_b32_e32 v73, 0xffff0000, v43
	v_lshlrev_b32_e32 v76, 16, v42
	v_and_b32_e32 v77, 0xffff0000, v42
	v_lshlrev_b32_e32 v40, 16, v59
	v_and_b32_e32 v41, 0xffff0000, v59
	v_lshlrev_b32_e32 v42, 16, v58
	v_and_b32_e32 v43, 0xffff0000, v58
	v_lshlrev_b32_e32 v58, 16, v57
	v_and_b32_e32 v59, 0xffff0000, v57
	v_lshlrev_b32_e32 v96, 16, v56
	v_and_b32_e32 v97, 0xffff0000, v56
	v_pk_mul_f32 v[56:57], v[46:47], v[46:47]
	v_pk_mul_f32 v[98:99], v[82:83], v[82:83]
	v_lshlrev_b32_e32 v90, 16, v55
	v_and_b32_e32 v91, 0xffff0000, v55
	v_lshlrev_b32_e32 v92, 16, v54
	v_and_b32_e32 v93, 0xffff0000, v54
	v_lshlrev_b32_e32 v54, 16, v53
	v_and_b32_e32 v55, 0xffff0000, v53
	v_lshlrev_b32_e32 v94, 16, v52
	v_and_b32_e32 v95, 0xffff0000, v52
	v_pk_mul_f32 v[52:53], v[76:77], v[76:77]
	v_add_f32_e32 v56, v56, v57
	v_add_f32_e32 v57, v98, v99
	v_lshlrev_b32_e32 v84, 16, v51
	v_and_b32_e32 v85, 0xffff0000, v51
	v_lshlrev_b32_e32 v86, 16, v50
	v_and_b32_e32 v87, 0xffff0000, v50
	v_lshlrev_b32_e32 v50, 16, v49
	v_and_b32_e32 v51, 0xffff0000, v49
	v_lshlrev_b32_e32 v88, 16, v48
	v_and_b32_e32 v89, 0xffff0000, v48
	v_pk_mul_f32 v[48:49], v[72:73], v[72:73]
	v_add_f32_e32 v81, v52, v53
	v_add_f32_e32 v56, v57, v56
	v_pk_mul_f32 v[106:107], v[88:89], v[88:89]
	v_add_f32_e32 v98, v48, v49
	v_add_f32_e32 v56, v81, v56
	v_pk_mul_f32 v[104:105], v[50:51], v[50:51]
	v_add_f32_e32 v99, v106, v107
	v_add_f32_e32 v56, v98, v56
	v_pk_mul_f32 v[102:103], v[86:87], v[86:87]
	v_add_f32_e32 v104, v104, v105
	v_add_f32_e32 v56, v99, v56
	v_pk_mul_f32 v[100:101], v[84:85], v[84:85]
	v_add_f32_e32 v102, v102, v103
	v_add_f32_e32 v56, v104, v56
	v_pk_mul_f32 v[114:115], v[94:95], v[94:95]
	v_add_f32_e32 v100, v100, v101
	v_add_f32_e32 v56, v102, v56
	v_pk_mul_f32 v[112:113], v[54:55], v[54:55]
	v_add_f32_e32 v101, v114, v115
	v_add_f32_e32 v56, v100, v56
	v_pk_mul_f32 v[110:111], v[92:93], v[92:93]
	v_add_f32_e32 v103, v112, v113
	v_add_f32_e32 v56, v101, v56
	v_pk_mul_f32 v[108:109], v[90:91], v[90:91]
	v_mov_b32_e32 v122, v59
	v_mov_b32_e32 v123, v97
	v_add_f32_e32 v105, v110, v111
	v_add_f32_e32 v56, v103, v56
	v_mov_b32_e32 v120, v58
	v_mov_b32_e32 v121, v96
	v_pk_mul_f32 v[122:123], v[122:123], v[122:123]
	v_add_f32_e32 v106, v108, v109
	v_add_f32_e32 v56, v105, v56
	v_mov_b32_e32 v118, v41
	v_mov_b32_e32 v119, v43
	v_pk_fma_f32 v[52:53], v[120:121], v[120:121], v[122:123]
	v_add_f32_e32 v56, v106, v56
	v_mov_b32_e32 v116, v40
	v_mov_b32_e32 v117, v42
	v_pk_mul_f32 v[118:119], v[118:119], v[118:119]
	v_add_f32_e32 v53, v53, v56
	v_pk_fma_f32 v[48:49], v[116:117], v[116:117], v[118:119]
	v_add_f32_e32 v52, v52, v53
	v_add_f32_e32 v49, v49, v52
	v_add_f32_e32 v53, v48, v49
	ds_bpermute_b32 v56, v216, v53
	v_lshlrev_b32_e32 v48, 16, v44
	v_and_b32_e32 v49, 0xffff0000, v44
	v_lshlrev_b32_e32 v80, 16, v45
	v_and_b32_e32 v81, 0xffff0000, v45
	s_waitcnt lgkmcnt(0)
	v_add_f32_e32 v44, v53, v56
	ds_bpermute_b32 v45, v217, v44
	v_lshlrev_b32_e32 v106, 16, v68
	v_and_b32_e32 v107, 0xffff0000, v68
	v_lshlrev_b32_e32 v52, 16, v63
	v_and_b32_e32 v53, 0xffff0000, v63
	s_waitcnt lgkmcnt(0)
	v_add_f32_e32 v44, v44, v45
	ds_bpermute_b32 v45, v218, v44
	v_lshlrev_b32_e32 v56, 16, v62
	v_and_b32_e32 v57, 0xffff0000, v62
	v_lshlrev_b32_e32 v62, 16, v61
	v_and_b32_e32 v63, 0xffff0000, v61
	s_waitcnt lgkmcnt(0)
	v_add_f32_e32 v44, v44, v45
	ds_bpermute_b32 v45, v219, v44
	v_lshlrev_b32_e32 v98, 16, v60
	v_and_b32_e32 v99, 0xffff0000, v60
	v_lshlrev_b32_e32 v60, 16, v67
	v_and_b32_e32 v61, 0xffff0000, v67
	s_waitcnt lgkmcnt(0)
	v_add_f32_e32 v44, v44, v45
	ds_bpermute_b32 v45, v220, v44
	v_lshlrev_b32_e32 v100, 16, v66
	v_and_b32_e32 v101, 0xffff0000, v66
	v_lshlrev_b32_e32 v66, 16, v65
	v_and_b32_e32 v67, 0xffff0000, v65
	s_waitcnt lgkmcnt(0)
	v_add_f32_e32 v44, v44, v45
	ds_bpermute_b32 v45, v221, v44
	v_lshlrev_b32_e32 v102, 16, v64
	v_and_b32_e32 v103, 0xffff0000, v64
	v_lshlrev_b32_e32 v64, 16, v71
	v_and_b32_e32 v65, 0xffff0000, v71
	s_waitcnt lgkmcnt(0)
; DEV unsigned cvtpk(float lo, float hi) { f32x2_t v = {lo, hi}; bf16x2_t b = __builtin_convertvector(v, bf16x2_t); return __builtin_bit_cast(unsigned, b); }
; DEV float wave_sum(float v) { for (int o = 32; o >= 1; o >>= 1) v += __shfl_xor(v, o); return v; }
; DEV void post_rows(const Params& p, const float* __restrict__ xsrc, const float* __restrict__ g, bool final) {
;     ...
;     const float rm = rsqrtf(ss * (1.f / DM) + EPS);
;     float sx = 0;
; #pragma unroll
;     for (int c = 0; c < 4; ++c) { const int idx = c * 512 + lane * 8;
;       float xo[8];
;       if (xsrc) { const f32x4 a = *reinterpret_cast<const f32x4*>(xsrc + (size_t)row * DM + idx), b = *reinterpret_cast<const f32x4*>(xsrc + (size_t)row * DM + idx + 4);
; #pragma unroll
;         for (int e = 0; e < 4; ++e) { xo[e] = a[e]; xo[4 + e] = b[e]; } }
;       else { const u32x4 w = *reinterpret_cast<const u32x4*>(xb + (size_t)row * DM + idx);
; #pragma unroll
;         for (int e = 0; e < 4; ++e) { xo[2 * e] = __uint_as_float(w[e] << 16); xo[2 * e + 1] = __uint_as_float(w[e] & 0xffff0000u); } }
;       const f32x4 g0 = *reinterpret_cast<const f32x4*>(g + idx), g1 = *reinterpret_cast<const f32x4*>(g + idx + 4);
;       float xn[8];
; #pragma unroll
;       for (int e = 0; e < 4; ++e) { xn[e] = xo[e] + mv[c * 8 + e] * rm * g0[e]; xn[4 + e] = xo[4 + e] + mv[c * 8 + 4 + e] * rm * g1[e]; }
;       if (final) { *reinterpret_cast<f32x4*>(p.out + (size_t)row * DM + idx) = (f32x4){xn[0], xn[1], xn[2], xn[3]};
;                    *reinterpret_cast<f32x4*>(p.out + (size_t)row * DM + idx + 4) = (f32x4){xn[4], xn[5], xn[6], xn[7]}; }
;       else { const u32x4 w = {cvtpk(xn[0], xn[1]), cvtpk(xn[2], xn[3]), cvtpk(xn[4], xn[5]), cvtpk(xn[6], xn[7])};
;         *reinterpret_cast<u32x4*>(xb + (size_t)row * DM + idx) = w;
; #pragma unroll
;         for (int e = 0; e < 4; ++e) { const float lo = __uint_as_float(w[e] << 16), hi = __uint_as_float(w[e] & 0xffff0000u); sx += lo * lo + hi * hi; } } }
;     if (!final) { sx = wave_sum(sx); if (lane == 0) rstd[row] = rsqrtf(sx * (1.f / DM) + EPS); }
	v_add_f32_e32 v44, v44, v45
	v_mov_b32_e32 v45, 0x358637bd
	v_fmamk_f32 v44, v44, 0x3a000000, v45
	v_mul_f32_e32 v45, 0x4b800000, v44
	v_cmp_gt_f32_e64 s[0:1], s33, v44
	v_lshlrev_b32_e32 v104, 16, v70
	v_and_b32_e32 v105, 0xffff0000, v70
	v_cndmask_b32_e64 v44, v44, v45, s[0:1]
	v_rsq_f32_e32 v44, v44
	v_lshlrev_b32_e32 v70, 16, v69
	v_and_b32_e32 v71, 0xffff0000, v69
	v_mul_f32_e32 v45, 0x45800000, v44
	v_cndmask_b32_e64 v68, v44, v45, s[0:1]
	v_pk_mul_f32 v[44:45], v[68:69], v[82:83] op_sel_hi:[0,1]
	v_pk_fma_f32 v[44:45], v[0:1], v[44:45], v[48:49]
	v_pk_mul_f32 v[48:49], v[68:69], v[76:77] op_sel_hi:[0,1]
	v_pk_mul_f32 v[46:47], v[68:69], v[46:47] op_sel_hi:[0,1]
	v_pk_fma_f32 v[48:49], v[4:5], v[48:49], v[78:79]
	v_pk_fma_f32 v[46:47], v[2:3], v[46:47], v[80:81]
	v_cvt_pk_bf16_f32 v44, v44, v45
	v_cvt_pk_bf16_f32 v45, v46, v47
	v_cvt_pk_bf16_f32 v46, v48, v49
	v_and_b32_e32 v49, 0xffff0000, v44
	v_pk_mul_f32 v[72:73], v[68:69], v[72:73] op_sel_hi:[0,1]
	v_lshlrev_b32_e32 v48, 16, v44
	v_mul_f32_e32 v49, v49, v49
	v_and_b32_e32 v69, 0xffff0000, v45
	v_fmac_f32_e32 v49, v48, v48
	v_lshlrev_b32_e32 v48, 16, v45
	v_mul_f32_e32 v69, v69, v69
	v_fmac_f32_e32 v69, v48, v48
	v_add_f32_e32 v48, v49, v69
	v_and_b32_e32 v69, 0xffff0000, v46
	v_pk_fma_f32 v[72:73], v[6:7], v[72:73], v[74:75]
	v_lshlrev_b32_e32 v49, 16, v46
	v_mul_f32_e32 v69, v69, v69
	v_cvt_pk_bf16_f32 v47, v72, v73
	v_fmac_f32_e32 v69, v49, v49
	v_add_f32_e32 v48, v69, v48
	v_and_b32_e32 v69, 0xffff0000, v47
	v_lshlrev_b32_e32 v49, 16, v47
	v_mul_f32_e32 v69, v69, v69
	v_fmac_f32_e32 v69, v49, v49
	v_add_f32_e32 v69, v69, v48
	v_pk_mul_f32 v[48:49], v[68:69], v[88:89] op_sel_hi:[0,1]
	v_pk_mul_f32 v[50:51], v[68:69], v[50:51] op_sel_hi:[0,1]
	v_pk_fma_f32 v[48:49], v[8:9], v[48:49], v[98:99]
	v_pk_fma_f32 v[50:51], v[10:11], v[50:51], v[62:63]
	v_pk_mul_f32 v[62:63], v[68:69], v[84:85] op_sel_hi:[0,1]
	v_pk_fma_f32 v[52:53], v[14:15], v[62:63], v[52:53]
	v_cvt_pk_bf16_f32 v48, v48, v49
	v_pk_mul_f32 v[72:73], v[68:69], v[86:87] op_sel_hi:[0,1]
	v_cvt_pk_bf16_f32 v49, v50, v51
	v_cvt_pk_bf16_f32 v51, v52, v53
	v_and_b32_e32 v53, 0xffff0000, v48
	v_pk_fma_f32 v[56:57], v[12:13], v[72:73], v[56:57]
	v_lshlrev_b32_e32 v52, 16, v48
	v_mul_f32_e32 v53, v53, v53
	v_cvt_pk_bf16_f32 v50, v56, v57
	v_fmac_f32_e32 v53, v52, v52
	v_and_b32_e32 v56, 0xffff0000, v49
	v_add_f32_e32 v52, v53, v69
	v_lshlrev_b32_e32 v53, 16, v49
	v_mul_f32_e32 v56, v56, v56
	v_fmac_f32_e32 v56, v53, v53
	v_add_f32_e32 v52, v56, v52
	v_and_b32_e32 v56, 0xffff0000, v50
	v_lshlrev_b32_e32 v53, 16, v50
	v_mul_f32_e32 v56, v56, v56
	v_fmac_f32_e32 v56, v53, v53
	v_add_f32_e32 v52, v56, v52
	v_and_b32_e32 v56, 0xffff0000, v51
	v_lshlrev_b32_e32 v53, 16, v51
	v_mul_f32_e32 v56, v56, v56
	v_fmac_f32_e32 v56, v53, v53
	v_add_f32_e32 v69, v56, v52
	v_pk_mul_f32 v[52:53], v[68:69], v[94:95] op_sel_hi:[0,1]
	v_pk_fma_f32 v[52:53], v[16:17], v[52:53], v[102:103]
	v_pk_mul_f32 v[56:57], v[68:69], v[92:93] op_sel_hi:[0,1]
	v_pk_mul_f32 v[54:55], v[68:69], v[54:55] op_sel_hi:[0,1]
	v_pk_fma_f32 v[56:57], v[20:21], v[56:57], v[100:101]
	v_pk_fma_f32 v[54:55], v[18:19], v[54:55], v[66:67]
	v_cvt_pk_bf16_f32 v52, v52, v53
	v_pk_mul_f32 v[62:63], v[68:69], v[90:91] op_sel_hi:[0,1]
	v_cvt_pk_bf16_f32 v53, v54, v55
	v_cvt_pk_bf16_f32 v54, v56, v57
	v_and_b32_e32 v57, 0xffff0000, v52
	v_pk_fma_f32 v[60:61], v[22:23], v[62:63], v[60:61]
	v_lshlrev_b32_e32 v56, 16, v52
	v_mul_f32_e32 v57, v57, v57
	v_cvt_pk_bf16_f32 v55, v60, v61
	v_fmac_f32_e32 v57, v56, v56
	v_and_b32_e32 v60, 0xffff0000, v53
	v_add_f32_e32 v56, v57, v69
	v_lshlrev_b32_e32 v57, 16, v53
	v_mul_f32_e32 v60, v60, v60
	v_fmac_f32_e32 v60, v57, v57
	v_add_f32_e32 v56, v60, v56
	v_and_b32_e32 v60, 0xffff0000, v54
	v_lshlrev_b32_e32 v57, 16, v54
	v_mul_f32_e32 v60, v60, v60
	v_fmac_f32_e32 v60, v57, v57
	v_add_f32_e32 v56, v60, v56
	v_and_b32_e32 v60, 0xffff0000, v55
	v_lshlrev_b32_e32 v57, 16, v55
	v_mul_f32_e32 v60, v60, v60
	v_fmac_f32_e32 v60, v57, v57
	v_add_f32_e32 v60, v60, v56
	v_pk_mul_f32 v[56:57], v[68:69], v[96:97] op_sel_hi:[0,1]
	v_pk_fma_f32 v[56:57], v[24:25], v[56:57], v[106:107]
	v_pk_mul_f32 v[58:59], v[68:69], v[58:59] op_sel_hi:[0,1]
	v_pk_mul_f32 v[40:41], v[68:69], v[40:41] op_sel_hi:[0,1]
	v_pk_fma_f32 v[58:59], v[26:27], v[58:59], v[70:71]
	v_pk_fma_f32 v[40:41], v[30:31], v[40:41], v[64:65]
	v_cvt_pk_bf16_f32 v56, v56, v57
	v_pk_mul_f32 v[42:43], v[68:69], v[42:43] op_sel_hi:[0,1]
	v_cvt_pk_bf16_f32 v57, v58, v59
	v_cvt_pk_bf16_f32 v59, v40, v41
	v_and_b32_e32 v41, 0xffff0000, v56
	v_pk_fma_f32 v[42:43], v[28:29], v[42:43], v[104:105]
	v_lshlrev_b32_e32 v40, 16, v56
	v_mul_f32_e32 v41, v41, v41
	v_cvt_pk_bf16_f32 v58, v42, v43
	v_fmac_f32_e32 v41, v40, v40
	v_and_b32_e32 v42, 0xffff0000, v57
	v_add_f32_e32 v40, v41, v60
	v_lshlrev_b32_e32 v41, 16, v57
	v_mul_f32_e32 v42, v42, v42
	v_fmac_f32_e32 v42, v41, v41
	v_add_f32_e32 v40, v42, v40
	v_and_b32_e32 v42, 0xffff0000, v58
	v_lshlrev_b32_e32 v41, 16, v58
	v_mul_f32_e32 v42, v42, v42
	v_fmac_f32_e32 v42, v41, v41
	v_add_f32_e32 v40, v42, v40
	v_and_b32_e32 v42, 0xffff0000, v59
	v_lshlrev_b32_e32 v41, 16, v59
	v_mul_f32_e32 v42, v42, v42
	v_fmac_f32_e32 v42, v41, v41
	v_add_f32_e32 v40, v42, v40
	ds_bpermute_b32 v41, v216, v40
	global_store_dwordx4 v[38:39], v[44:47], off
	global_store_dwordx4 v[38:39], v[48:51], off offset:1024
	global_store_dwordx4 v[38:39], v[52:55], off offset:2048
	global_store_dwordx4 v[38:39], v[56:59], off offset:3072
	s_waitcnt lgkmcnt(0)
	v_add_f32_e32 v40, v40, v41
	ds_bpermute_b32 v41, v217, v40
	s_waitcnt lgkmcnt(0)
	v_add_f32_e32 v40, v40, v41
	ds_bpermute_b32 v41, v218, v40
	s_waitcnt lgkmcnt(0)
	v_add_f32_e32 v40, v40, v41
	ds_bpermute_b32 v41, v219, v40
	s_waitcnt lgkmcnt(0)
	v_add_f32_e32 v40, v40, v41
	ds_bpermute_b32 v41, v220, v40
	s_waitcnt lgkmcnt(0)
	v_add_f32_e32 v40, v40, v41
	ds_bpermute_b32 v41, v221, v40
	s_and_saveexec_b64 s[10:11], vcc
	s_cbranch_execz .LBB0_554
	s_waitcnt lgkmcnt(0)
	v_add_f32_e32 v38, v40, v41
	v_mov_b32_e32 v39, 0x358637bd
	v_fmamk_f32 v38, v38, 0x3a000000, v39
	v_mul_f32_e32 v39, 0x4b800000, v38
	v_cmp_gt_f32_e64 s[0:1], s33, v38
	s_nop 1
	v_cndmask_b32_e64 v38, v38, v39, s[0:1]
	v_rsq_f32_e32 v38, v38
	s_nop 0
	v_mul_f32_e32 v39, 0x45800000, v38
	v_cndmask_b32_e64 v40, v38, v39, s[0:1]
	v_lshl_add_u64 v[38:39], v[32:33], 2, s[68:69]
	global_store_dword v[38:39], v40, off
	s_branch .LBB0_554
